# peel + all three GEMMs: first two load-segment waits of each unit relaxed by the epilogue store count (stores need not retire before the first MFMA blocks)
# baseline (speedup 1.0000x reference)
; #define PG8_STAGE(bufoff, gbase, voff) do { _Pragma("unroll") for (int _i = 0; _i < 2; ++_i) \
;         __builtin_amdgcn_global_load_lds((const unsigned*)((const char*)(gbase) + (voff)[_i]), (PG8_LAS unsigned*)(lds + (bufoff) + ldsw + _i * 8192), 16, 0, 0); } while (0)
; #define PG8_WAIT_V(n) asm volatile("s_waitcnt vmcnt(" #n ")" ::: "memory")
; #define PG8_BAR __builtin_amdgcn_s_barrier()
; template <class Epi, class Sched, bool ALIGN_EPI = false, bool SP2 = false>
; __device__ __forceinline__ void gemm_phase(PG8_LAS unsigned char* lds, const Gemm g, const Sched& S, const Epi& E) {
;     ...
;     const int wid = __builtin_amdgcn_readfirstlane(tid >> 6), lane = tid & 63, wr = wid >> 2, wc = wid & 3, fr = lane & 15, fq = lane >> 4;
;     const int K = g.K, nt = K / BK;
;     unsigned voffA[2], voffB[2];
; #pragma unroll
;     for (int i = 0; i < 2; ++i) { int R, C; stage_rc(tid * 16 + i * 8192, R, C); const int Rb = Epi::PERM ? ((R & ~31) + perm32(R & 31)) : R;
;         voffA[i] = g.tiledA ? (unsigned)((C >> 5) * 8192 + R * 64 + (C & 31) * 2) : (unsigned)(R * K + C) * 2u; voffB[i] = (unsigned)(Rb * K + C) * 2u; }
;     const size_t kstep = (size_t)(BK * 2);
;     const size_t kstepA = g.tiledA ? (size_t)16384 : kstep;
;     const size_t hstep = (size_t)HALF * K * 2;
;     const size_t tstep = 2 * hstep;
;     const unsigned ldsw = (unsigned)wid * 1024u;
;     const int aoff = lds_byte(wr * 64 + fr, fq * 8), boff = lds_byte(wc * 32 + fr, fq * 8);
;     ...
;         PG8_STAGE(PG8_SB(0, 0), cB, voffB); PG8_STAGE(PG8_SB(0, 1), cB + hstep, voffB); PG8_STAGE(PG8_SA(0, 0), cA, voffA); PG8_STAGE(PG8_SA(0, 1), cA + hstep, voffA);
;         if (wr == 1) PG8_BAR;
;         PG8_WAIT_V(2); PG8_BAR;
;         PG8_STAGE(PG8_SB(1, 0), cB + kstep, voffB); PG8_STAGE(PG8_SA(1, 0), cA + kstepA, voffA); PG8_STAGE(PG8_SB(1, 1), cB + hstep + kstep, voffB);
;         PG8_WAIT_V(6); PG8_BAR;
.LBB0_232:
	v_and_b32_e32 v15, 15, v0
	v_lshrrev_b32_e32 v0, 1, v0
	s_and_b64 s[2:3], s[2:3], exec
	v_and_b32_e32 v14, 24, v0
	s_cselect_b32 s59, 56, 32
	s_cselect_b32 s60, 4, 0
	s_cselect_b32 s61, 0x3e8, 4
	s_add_u32 s62, s30, 0xc000000
	v_lshlrev_b32_e32 v0, 1, v14
	v_lshlrev_b32_e32 v16, 2, v15
	s_addc_u32 s63, s31, 0
	s_and_b32 s34, s7, 3
	v_lshl_or_b32 v0, v15, 6, v0
	s_lshl_b32 s2, s8, 13
	v_and_b32_e32 v17, 32, v16
	s_add_i32 m0, s23, 0x18000
	v_lshl_add_u64 v[2:3], v[2:3], 0, s[38:39]
	v_bitop3_b32 v18, v0, s2, v17 bitop3:0xde
	s_lshl_b32 s2, s34, 12
	s_waitcnt vmcnt(2)
	s_barrier
	global_load_lds_dwordx4 v[2:3], off
	s_add_i32 m0, s23, 0x1a000
	v_bitop3_b32 v150, v0, s2, v17 bitop3:0xde
	s_add_u32 s2, s24, 0x4000
	v_mov_b32_e32 v131, v1
	v_lshl_add_u64 v[2:3], v[4:5], 0, s[38:39]
	s_addc_u32 s3, s25, 0
	s_add_i32 s64, s23, 0x8000
	v_mov_b32_e32 v135, v1
	global_load_lds_dwordx4 v[2:3], off
	v_lshl_add_u64 v[2:3], s[2:3], 0, v[130:131]
	s_mov_b32 m0, s64
	s_add_i32 s65, s23, 0xa000
	global_load_lds_dwordx4 v[2:3], off
	v_lshl_add_u64 v[2:3], s[2:3], 0, v[134:135]
	s_add_u32 s2, s26, 0x40080
	s_mov_b32 m0, s65
	s_addc_u32 s3, s27, 0
	global_load_lds_dwordx4 v[2:3], off
	s_add_i32 m0, s23, 0x1c000
	v_lshl_add_u64 v[2:3], s[2:3], 0, v[132:133]
	global_load_lds_dwordx4 v[2:3], off
	v_lshl_add_u64 v[2:3], s[2:3], 0, v[136:137]
	s_add_i32 m0, s23, 0x1e000
	s_cmpk_lt_u32 s6, 0x100
	global_load_lds_dwordx4 v[2:3], off
	v_lshlrev_b32_e32 v0, 5, v15
	s_cselect_b64 s[6:7], -1, 0
	v_lshl_or_b32 v138, s8, 11, v0
	s_lshl_b32 s2, s8, 8
	v_lshlrev_b32_e32 v0, 9, v10
	s_add_i32 s2, s2, 0
	v_and_b32_e32 v0, 0xfffffc00, v0
	s_add_i32 s2, s2, 0x20000
	v_add_u32_e32 v0, v12, v0
	v_add_u32_e32 v151, s2, v16
	v_add3_u32 v0, v0, v11, v13
	s_mov_b64 s[2:3], 0x44000
	v_lshl_add_u64 v[140:141], v[0:1], 0, s[2:3]
	v_lshlrev_b32_e32 v0, 9, v6
	v_and_b32_e32 v0, 0xfffffc00, v0
	s_waitcnt vmcnt(6)
	v_add_u32_e32 v0, v8, v0
	v_add3_u32 v0, v0, v7, v9
	s_mov_b32 s21, 0
	v_ashrrev_i32_e32 v139, 31, v138
	v_lshl_add_u64 v[142:143], v[0:1], 0, s[2:3]
	v_add_u32_e32 v152, 0, v18
	v_lshlrev_b32_e32 v0, 1, v14
	s_waitcnt vmcnt(0)
	s_barrier
	s_branch .LBB0_235

; #define PG8_STAGE(bufoff, gbase, voff) do { _Pragma("unroll") for (int _i = 0; _i < 2; ++_i) \
;         __builtin_amdgcn_global_load_lds((const unsigned*)((const char*)(gbase) + (voff)[_i]), (PG8_LAS unsigned*)(lds + (bufoff) + ldsw + _i * 8192), 16, 0, 0); } while (0)
; #define PG8_LDA(dst, b, h) do { _Pragma("unroll") for (int m = 0; m < 4; ++m) _Pragma("unroll") for (int k = 0; k < 2; ++k) dst[m][k] = *(const PG8_LAS bf16x8*)(lds + PG8_SA(b, h) + aoff + m * 2048 + k * 1024); } while (0)
; #define PG8_LDB(dst, b, h) do { _Pragma("unroll") for (int n = 0; n < 2; ++n) _Pragma("unroll") for (int k = 0; k < 2; ++k) dst[n][k] = *(const PG8_LAS bf16x8*)(lds + PG8_SB(b, h) + boff + n * 2048 + k * 1024); } while (0)
; #define PG8_WAIT_V(n) asm volatile("s_waitcnt vmcnt(" #n ")" ::: "memory")
; #define PG8_WAIT_L(n) asm volatile("s_waitcnt lgkmcnt(" #n ")" ::: "memory")
; #define PG8_BAR __builtin_amdgcn_s_barrier()
; #define PG8_SCHED __builtin_amdgcn_sched_barrier(0)
; template <class Epi, class Sched, bool ALIGN_EPI = false, bool SP2 = false>
; __device__ __forceinline__ void gemm_phase(PG8_LAS unsigned char* lds, const Gemm g, const Sched& S, const Epi& E) {
;     ...
;         const char* nA = has_next ? (const char*)g.A + (size_t)nxt.pm * tstep : cA; const char* nB = has_next ? (const char*)g.Bt + (size_t)nxt.pn * tstep : cB;
;         for (int t = 0; t < nt; t += 2) {
;             const bool last = (t == nt - 2);
;             const char* a1 = cA + (size_t)(t + 1) * kstepA;
;             const char* a2 = last ? nA : cA + (size_t)(t + 2) * kstepA; const char* b2 = last ? nB : cB + (size_t)(t + 2) * kstep;
;             const char* a3 = a2 + kstepA; const char* b3 = b2 + kstep;
;             if (last && has_next) S.a_ready(nxt);
;             if constexpr (SP2) {
;             PG8_LDB(B0, 0, 0); PG8_LDB(B1, 0, 1); PG8_SCHED; PG8_LDA(At, 0, 0); PG8_STAGE(PG8_SA(1, 1), a1 + hstep, voffA);
;             PG8_WAIT_V(8); PG8_WAIT_L(0); PG8_BAR; PG8_MMA(0, 0, At, B0); PG8_MMA(0, 1, At, B1); PG8_BAR; PG8_SCHED;
;             PG8_LDA(At, 0, 1); PG8_STAGE(PG8_SB(0, 0), b2, voffB); PG8_STAGE(PG8_SB(0, 1), b2 + hstep, voffB); PG8_STAGE(PG8_SA(0, 0), a2, voffA);
;             PG8_WAIT_V(8); PG8_WAIT_L(0); PG8_BAR; PG8_MMA(1, 0, At, B0); PG8_MMA(1, 1, At, B1); PG8_BAR; PG8_SCHED;
.LBB0_237:
	s_ashr_i32 s11, s10, 31
	s_lshl_b64 s[2:3], s[10:11], 19
	s_add_u32 s12, s52, s2
	s_addc_u32 s13, s53, s3
	s_and_b64 s[2:3], s[40:41], exec
	s_cselect_b32 s11, s13, s25
	s_cselect_b32 s67, s12, s24
	s_ashr_i32 s9, s8, 31
	s_lshl_b64 s[2:3], s[8:9], 19
	s_add_u32 s44, s54, s2
	s_addc_u32 s45, s55, s3
	s_and_b64 s[2:3], s[40:41], exec
	s_cselect_b32 s9, s45, s27
	s_cselect_b32 s68, s44, s26
	s_add_u32 s69, s26, 0x100
	s_addc_u32 s70, s27, 0
	s_mov_b32 s71, -2
	s_add_u32 s2, s24, 0x8000
	s_addc_u32 s3, s25, 0
	s_cmp_eq_u32 s71, 12
	s_cselect_b32 s46, s67, s2
	s_cselect_b32 s47, s11, s3
	s_cselect_b32 s42, s68, s69
	s_cselect_b32 s43, s9, s70
	s_add_u32 s26, s46, 0x4000
	s_addc_u32 s27, s47, 0
	v_add_u32_e32 v148, s76, v150
	s_add_i32 s72, 0, 0x14000
	ds_read_b128 v[144:147], v148
	ds_read_b128 v[160:163], v148 offset:1024
	ds_read_b128 v[164:167], v148 offset:2048
	ds_read_b128 v[168:171], v148 offset:3072
	v_add_u32_e32 v148, s72, v150
	ds_read_b128 v[172:175], v148
	ds_read_b128 v[176:179], v148 offset:1024
	ds_read_b128 v[180:183], v148 offset:2048
	ds_read_b128 v[184:187], v148 offset:3072
	v_lshl_add_u64 v[148:149], s[24:25], 0, v[142:143]
	s_add_i32 m0, s23, 0xc000
	ds_read_b128 v[188:191], v152
	ds_read_b128 v[206:209], v152 offset:1024
	ds_read_b128 v[210:213], v152 offset:2048
	ds_read_b128 v[214:217], v152 offset:3072
	ds_read_b128 v[218:221], v152 offset:4096
	ds_read_b128 v[222:225], v152 offset:5120
	ds_read_b128 v[226:229], v152 offset:6144
	ds_read_b128 v[230:233], v152 offset:7168
	global_load_lds_dwordx4 v[148:149], off
	v_lshl_add_u64 v[148:149], s[24:25], 0, v[140:141]
	s_add_i32 m0, s23, 0xe000
	s_nop 0
	global_load_lds_dwordx4 v[148:149], off
	s_waitcnt vmcnt(24)
	s_waitcnt lgkmcnt(0)
	s_barrier
	v_mfma_f32_16x16x32_bf16 v[126:129], v[144:147], v[188:191], 0
	v_mfma_f32_16x16x32_bf16 v[126:129], v[160:163], v[206:209], v[126:129]
	v_mfma_f32_16x16x32_bf16 v[122:125], v[168:171], v[206:209], 0
	v_mfma_f32_16x16x32_bf16 v[122:125], v[164:167], v[188:191], v[122:125]
	v_mfma_f32_16x16x32_bf16 v[106:109], v[164:167], v[210:213], 0
	v_mfma_f32_16x16x32_bf16 v[106:109], v[168:171], v[214:217], v[106:109]
	v_mfma_f32_16x16x32_bf16 v[110:113], v[160:163], v[214:217], 0
	v_mfma_f32_16x16x32_bf16 v[110:113], v[144:147], v[210:213], v[110:113]
	v_mfma_f32_16x16x32_bf16 v[94:97], v[144:147], v[218:221], 0
	v_mfma_f32_16x16x32_bf16 v[94:97], v[160:163], v[222:225], v[94:97]
	v_mfma_f32_16x16x32_bf16 v[90:93], v[168:171], v[222:225], 0
	v_mfma_f32_16x16x32_bf16 v[90:93], v[164:167], v[218:221], v[90:93]
	v_mfma_f32_16x16x32_bf16 v[74:77], v[164:167], v[226:229], 0
	v_mfma_f32_16x16x32_bf16 v[74:77], v[168:171], v[230:233], v[74:77]
	v_mfma_f32_16x16x32_bf16 v[78:81], v[160:163], v[230:233], 0
	v_mfma_f32_16x16x32_bf16 v[78:81], v[144:147], v[226:229], v[78:81]
	v_mfma_f32_16x16x32_bf16 v[118:121], v[172:175], v[188:191], 0
	v_mfma_f32_16x16x32_bf16 v[118:121], v[176:179], v[206:209], v[118:121]
	v_mfma_f32_16x16x32_bf16 v[114:117], v[184:187], v[206:209], 0
	v_mfma_f32_16x16x32_bf16 v[114:117], v[180:183], v[188:191], v[114:117]
	v_mfma_f32_16x16x32_bf16 v[98:101], v[180:183], v[210:213], 0
	v_mfma_f32_16x16x32_bf16 v[98:101], v[184:187], v[214:217], v[98:101]
	v_mfma_f32_16x16x32_bf16 v[102:105], v[176:179], v[214:217], 0
	v_mfma_f32_16x16x32_bf16 v[102:105], v[172:175], v[210:213], v[102:105]
	v_mfma_f32_16x16x32_bf16 v[86:89], v[172:175], v[218:221], 0
	v_mfma_f32_16x16x32_bf16 v[86:89], v[176:179], v[222:225], v[86:89]
	v_mfma_f32_16x16x32_bf16 v[82:85], v[184:187], v[222:225], 0
	v_mfma_f32_16x16x32_bf16 v[82:85], v[180:183], v[218:221], v[82:85]
	v_mfma_f32_16x16x32_bf16 v[66:69], v[180:183], v[226:229], 0
	v_mfma_f32_16x16x32_bf16 v[66:69], v[184:187], v[230:233], v[66:69]
	v_mfma_f32_16x16x32_bf16 v[70:73], v[176:179], v[230:233], 0
	v_mfma_f32_16x16x32_bf16 v[70:73], v[172:175], v[226:229], v[70:73]
	s_barrier
	s_add_i32 s24, s76, s51
	v_lshl_add_u64 v[148:149], s[42:43], 0, v[132:133]
	s_mov_b32 m0, s24
	ds_read_b128 v[188:191], v152 offset:16384
	ds_read_b128 v[206:209], v152 offset:17408
	ds_read_b128 v[210:213], v152 offset:18432
	ds_read_b128 v[214:217], v152 offset:19456
	ds_read_b128 v[218:221], v152 offset:20480
	ds_read_b128 v[222:225], v152 offset:21504
	ds_read_b128 v[226:229], v152 offset:22528
	ds_read_b128 v[230:233], v152 offset:23552
	global_load_lds_dwordx4 v[148:149], off
	s_add_i32 m0, s24, 0x2000
	s_add_u32 s24, s42, 0x40000
	v_lshl_add_u64 v[234:235], s[42:43], 0, v[136:137]
	s_addc_u32 s25, s43, 0
	s_add_i32 s72, s72, s51
	global_load_lds_dwordx4 v[234:235], off
	v_lshl_add_u64 v[236:237], s[24:25], 0, v[132:133]
	s_mov_b32 m0, s72
	s_nop 0
	global_load_lds_dwordx4 v[236:237], off
	v_lshl_add_u64 v[236:237], s[24:25], 0, v[136:137]
	s_add_i32 m0, s72, 0x2000
	s_nop 0
	global_load_lds_dwordx4 v[236:237], off
	v_lshl_add_u64 v[236:237], s[46:47], 0, v[130:131]
	s_mov_b32 m0, s23
	s_nop 0
	global_load_lds_dwordx4 v[236:237], off
	v_lshl_add_u64 v[236:237], s[46:47], 0, v[134:135]
	s_mov_b32 m0, s56
	s_nop 0
	global_load_lds_dwordx4 v[236:237], off
	s_waitcnt vmcnt(24)
	s_waitcnt lgkmcnt(0)
	s_barrier
; #define PG8_STAGE(bufoff, gbase, voff) do { _Pragma("unroll") for (int _i = 0; _i < 2; ++_i) \
;         __builtin_amdgcn_global_load_lds((const unsigned*)((const char*)(gbase) + (voff)[_i]), (PG8_LAS unsigned*)(lds + (bufoff) + ldsw + _i * 8192), 16, 0, 0); } while (0)
; #define PG8_LDA(dst, b, h) do { _Pragma("unroll") for (int m = 0; m < 4; ++m) _Pragma("unroll") for (int k = 0; k < 2; ++k) dst[m][k] = *(const PG8_LAS bf16x8*)(lds + PG8_SA(b, h) + aoff + m * 2048 + k * 1024); } while (0)
; #define PG8_LDB(dst, b, h) do { _Pragma("unroll") for (int n = 0; n < 2; ++n) _Pragma("unroll") for (int k = 0; k < 2; ++k) dst[n][k] = *(const PG8_LAS bf16x8*)(lds + PG8_SB(b, h) + boff + n * 2048 + k * 1024); } while (0)
; #define PG8_MMA(ai, bj, At, Bt) do { __builtin_amdgcn_s_setprio(1); _Pragma("unroll") for (int m = 0; m < 4; ++m) _Pragma("unroll") for (int n = 0; n < 2; ++n) _Pragma("unroll") for (int k = 0; k < 2; ++k) \
;         acc[ai][bj][m][n] = __builtin_amdgcn_mfma_f32_16x16x32_bf16(Bt[n][k], At[m][k], acc[ai][bj][m][n], 0, 0, 0); __builtin_amdgcn_s_setprio(0); } while (0)
; #define PG8_WAIT_V(n) asm volatile("s_waitcnt vmcnt(" #n ")" ::: "memory")
; #define PG8_WAIT_L(n) asm volatile("s_waitcnt lgkmcnt(" #n ")" ::: "memory")
; #define PG8_BAR __builtin_amdgcn_s_barrier()
; #define PG8_SCHED __builtin_amdgcn_sched_barrier(0)
; template <class Epi, class Sched, bool ALIGN_EPI = false, bool SP2 = false>
; __device__ __forceinline__ void gemm_phase(PG8_LAS unsigned char* lds, const Gemm g, const Sched& S, const Epi& E) {
;     ...
;             PG8_WAIT_V(8); PG8_WAIT_L(0); PG8_BAR; PG8_MMA(1, 0, At, B0); PG8_MMA(1, 1, At, B1); PG8_BAR; PG8_SCHED;
;             PG8_LDB(B0, 1, 0); PG8_LDB(B1, 1, 1); PG8_SCHED; PG8_LDA(At, 1, 0); PG8_STAGE(PG8_SA(0, 1), a2 + hstep, voffA);
;             PG8_WAIT_V(8); PG8_WAIT_L(0); PG8_BAR; PG8_MMA(0, 0, At, B0); PG8_MMA(0, 1, At, B1); PG8_BAR; PG8_SCHED;
	v_mfma_f32_16x16x32_bf16 v[62:65], v[144:147], v[188:191], 0
	v_mfma_f32_16x16x32_bf16 v[62:65], v[160:163], v[206:209], v[62:65]
	v_mfma_f32_16x16x32_bf16 v[58:61], v[168:171], v[206:209], 0
	v_mfma_f32_16x16x32_bf16 v[58:61], v[164:167], v[188:191], v[58:61]
	v_mfma_f32_16x16x32_bf16 v[42:45], v[164:167], v[210:213], 0
	v_mfma_f32_16x16x32_bf16 v[42:45], v[168:171], v[214:217], v[42:45]
	v_mfma_f32_16x16x32_bf16 v[46:49], v[160:163], v[214:217], 0
	v_mfma_f32_16x16x32_bf16 v[46:49], v[144:147], v[210:213], v[46:49]
	v_mfma_f32_16x16x32_bf16 v[30:33], v[144:147], v[218:221], 0
	v_mfma_f32_16x16x32_bf16 v[30:33], v[160:163], v[222:225], v[30:33]
	v_mfma_f32_16x16x32_bf16 v[26:29], v[168:171], v[222:225], 0
	v_mfma_f32_16x16x32_bf16 v[26:29], v[164:167], v[218:221], v[26:29]
	v_mfma_f32_16x16x32_bf16 v[10:13], v[164:167], v[226:229], 0
	v_mfma_f32_16x16x32_bf16 v[10:13], v[168:171], v[230:233], v[10:13]
	v_mfma_f32_16x16x32_bf16 v[14:17], v[160:163], v[230:233], 0
	v_mfma_f32_16x16x32_bf16 v[14:17], v[144:147], v[226:229], v[14:17]
	v_mfma_f32_16x16x32_bf16 v[54:57], v[172:175], v[188:191], 0
	v_mfma_f32_16x16x32_bf16 v[54:57], v[176:179], v[206:209], v[54:57]
	v_mfma_f32_16x16x32_bf16 v[50:53], v[184:187], v[206:209], 0
	v_mfma_f32_16x16x32_bf16 v[50:53], v[180:183], v[188:191], v[50:53]
	v_mfma_f32_16x16x32_bf16 v[34:37], v[180:183], v[210:213], 0
	v_mfma_f32_16x16x32_bf16 v[34:37], v[184:187], v[214:217], v[34:37]
	v_mfma_f32_16x16x32_bf16 v[38:41], v[176:179], v[214:217], 0
	v_mfma_f32_16x16x32_bf16 v[38:41], v[172:175], v[210:213], v[38:41]
	v_mfma_f32_16x16x32_bf16 v[22:25], v[172:175], v[218:221], 0
	v_mfma_f32_16x16x32_bf16 v[22:25], v[176:179], v[222:225], v[22:25]
	v_mfma_f32_16x16x32_bf16 v[18:21], v[184:187], v[222:225], 0
	v_mfma_f32_16x16x32_bf16 v[18:21], v[180:183], v[218:221], v[18:21]
	v_mfma_f32_16x16x32_bf16 v[2:5], v[180:183], v[226:229], 0
	v_mfma_f32_16x16x32_bf16 v[2:5], v[184:187], v[230:233], v[2:5]
	v_mfma_f32_16x16x32_bf16 v[6:9], v[176:179], v[230:233], 0
	v_mfma_f32_16x16x32_bf16 v[6:9], v[172:175], v[226:229], v[6:9]
	s_barrier
	s_add_i32 s72, 0, 0x18000
	v_add_u32_e32 v153, s72, v150
	s_add_i32 s73, 0, 0x1c000
	ds_read_b128 v[144:147], v153
	ds_read_b128 v[160:163], v153 offset:1024
	ds_read_b128 v[164:167], v153 offset:2048
	ds_read_b128 v[168:171], v153 offset:3072
	v_add_u32_e32 v153, s73, v150
	ds_read_b128 v[172:175], v153
	ds_read_b128 v[176:179], v153 offset:1024
	ds_read_b128 v[180:183], v153 offset:2048
	ds_read_b128 v[184:187], v153 offset:3072
	s_add_u32 s24, s46, 0x40000
	s_addc_u32 s25, s47, 0
	s_mov_b32 m0, s57
	v_lshl_add_u64 v[236:237], s[24:25], 0, v[130:131]
	ds_read_b128 v[188:191], v152 offset:32768
	ds_read_b128 v[206:209], v152 offset:33792
	ds_read_b128 v[210:213], v152 offset:34816
	ds_read_b128 v[214:217], v152 offset:35840
	ds_read_b128 v[218:221], v152 offset:36864
	ds_read_b128 v[222:225], v152 offset:37888
	ds_read_b128 v[226:229], v152 offset:38912
	ds_read_b128 v[230:233], v152 offset:39936
	global_load_lds_dwordx4 v[236:237], off
	v_lshl_add_u64 v[236:237], s[24:25], 0, v[134:135]
	s_mov_b32 m0, s58
	s_nop 0
	global_load_lds_dwordx4 v[236:237], off
	s_waitcnt vmcnt(8)
	s_waitcnt lgkmcnt(0)
	s_barrier
	v_mfma_f32_16x16x32_bf16 v[126:129], v[144:147], v[188:191], v[126:129]
	v_mfma_f32_16x16x32_bf16 v[126:129], v[160:163], v[206:209], v[126:129]
	v_mfma_f32_16x16x32_bf16 v[122:125], v[168:171], v[206:209], v[122:125]
	v_mfma_f32_16x16x32_bf16 v[122:125], v[164:167], v[188:191], v[122:125]
	v_mfma_f32_16x16x32_bf16 v[106:109], v[164:167], v[210:213], v[106:109]
	v_mfma_f32_16x16x32_bf16 v[106:109], v[168:171], v[214:217], v[106:109]
	v_mfma_f32_16x16x32_bf16 v[110:113], v[160:163], v[214:217], v[110:113]
	v_mfma_f32_16x16x32_bf16 v[110:113], v[144:147], v[210:213], v[110:113]
	v_mfma_f32_16x16x32_bf16 v[94:97], v[144:147], v[218:221], v[94:97]
	v_mfma_f32_16x16x32_bf16 v[94:97], v[160:163], v[222:225], v[94:97]
	v_mfma_f32_16x16x32_bf16 v[90:93], v[168:171], v[222:225], v[90:93]
	v_mfma_f32_16x16x32_bf16 v[90:93], v[164:167], v[218:221], v[90:93]
	v_mfma_f32_16x16x32_bf16 v[74:77], v[164:167], v[226:229], v[74:77]
	v_mfma_f32_16x16x32_bf16 v[74:77], v[168:171], v[230:233], v[74:77]
	v_mfma_f32_16x16x32_bf16 v[78:81], v[160:163], v[230:233], v[78:81]
	v_mfma_f32_16x16x32_bf16 v[78:81], v[144:147], v[226:229], v[78:81]
	v_mfma_f32_16x16x32_bf16 v[118:121], v[172:175], v[188:191], v[118:121]
	v_mfma_f32_16x16x32_bf16 v[118:121], v[176:179], v[206:209], v[118:121]
	v_mfma_f32_16x16x32_bf16 v[114:117], v[184:187], v[206:209], v[114:117]
	v_mfma_f32_16x16x32_bf16 v[114:117], v[180:183], v[188:191], v[114:117]
	v_mfma_f32_16x16x32_bf16 v[98:101], v[180:183], v[210:213], v[98:101]
	v_mfma_f32_16x16x32_bf16 v[98:101], v[184:187], v[214:217], v[98:101]
	v_mfma_f32_16x16x32_bf16 v[102:105], v[176:179], v[214:217], v[102:105]
	v_mfma_f32_16x16x32_bf16 v[102:105], v[172:175], v[210:213], v[102:105]
	v_mfma_f32_16x16x32_bf16 v[86:89], v[172:175], v[218:221], v[86:89]
	v_mfma_f32_16x16x32_bf16 v[86:89], v[176:179], v[222:225], v[86:89]
	v_mfma_f32_16x16x32_bf16 v[82:85], v[184:187], v[222:225], v[82:85]
	v_mfma_f32_16x16x32_bf16 v[82:85], v[180:183], v[218:221], v[82:85]
	v_mfma_f32_16x16x32_bf16 v[66:69], v[180:183], v[226:229], v[66:69]
	v_mfma_f32_16x16x32_bf16 v[66:69], v[184:187], v[230:233], v[66:69]
	v_mfma_f32_16x16x32_bf16 v[70:73], v[176:179], v[230:233], v[70:73]
	v_mfma_f32_16x16x32_bf16 v[70:73], v[172:175], v[226:229], v[70:73]
	s_barrier
; #define PG8_STAGE(bufoff, gbase, voff) do { _Pragma("unroll") for (int _i = 0; _i < 2; ++_i) \
;         __builtin_amdgcn_global_load_lds((const unsigned*)((const char*)(gbase) + (voff)[_i]), (PG8_LAS unsigned*)(lds + (bufoff) + ldsw + _i * 8192), 16, 0, 0); } while (0)
; #define PG8_LDA(dst, b, h) do { _Pragma("unroll") for (int m = 0; m < 4; ++m) _Pragma("unroll") for (int k = 0; k < 2; ++k) dst[m][k] = *(const PG8_LAS bf16x8*)(lds + PG8_SA(b, h) + aoff + m * 2048 + k * 1024); } while (0)
; #define PG8_MMA(ai, bj, At, Bt) do { __builtin_amdgcn_s_setprio(1); _Pragma("unroll") for (int m = 0; m < 4; ++m) _Pragma("unroll") for (int n = 0; n < 2; ++n) _Pragma("unroll") for (int k = 0; k < 2; ++k) \
;         acc[ai][bj][m][n] = __builtin_amdgcn_mfma_f32_16x16x32_bf16(Bt[n][k], At[m][k], acc[ai][bj][m][n], 0, 0, 0); __builtin_amdgcn_s_setprio(0); } while (0)
; #define PG8_WAIT_V(n) asm volatile("s_waitcnt vmcnt(" #n ")" ::: "memory")
; #define PG8_WAIT_L(n) asm volatile("s_waitcnt lgkmcnt(" #n ")" ::: "memory")
; #define PG8_BAR __builtin_amdgcn_s_barrier()
; #define PG8_SCHED __builtin_amdgcn_sched_barrier(0)
; template <class Epi, class Sched, bool ALIGN_EPI = false, bool SP2 = false>
; __device__ __forceinline__ void gemm_phase(PG8_LAS unsigned char* lds, const Gemm g, const Sched& S, const Epi& E) {
;     ...
;             PG8_LDA(At, 1, 1); PG8_STAGE(PG8_SB(1, 0), b3, voffB); PG8_STAGE(PG8_SB(1, 1), b3 + hstep, voffB); PG8_STAGE(PG8_SA(1, 0), a3, voffA);
;             PG8_WAIT_V(8); PG8_WAIT_L(0); PG8_BAR; PG8_MMA(1, 0, At, B0); PG8_MMA(1, 1, At, B1); PG8_BAR; PG8_SCHED;
	s_add_i32 s24, s72, s51
	v_lshl_add_u64 v[148:149], v[148:149], 0, s[38:39]
	s_mov_b32 m0, s24
	ds_read_b128 v[188:191], v152 offset:49152
	ds_read_b128 v[206:209], v152 offset:50176
	ds_read_b128 v[210:213], v152 offset:51200
	ds_read_b128 v[214:217], v152 offset:52224
	ds_read_b128 v[218:221], v152 offset:53248
	ds_read_b128 v[222:225], v152 offset:54272
	ds_read_b128 v[226:229], v152 offset:55296
	ds_read_b128 v[230:233], v152 offset:56320
	global_load_lds_dwordx4 v[148:149], off
	s_add_i32 m0, s24, 0x2000
	s_add_u32 s24, s42, 0x40080
	v_lshl_add_u64 v[148:149], v[234:235], 0, s[38:39]
	s_addc_u32 s25, s43, 0
	s_add_i32 s42, s73, s51
	global_load_lds_dwordx4 v[148:149], off
	v_lshl_add_u64 v[148:149], s[24:25], 0, v[132:133]
	s_mov_b32 m0, s42
	s_nop 0
	global_load_lds_dwordx4 v[148:149], off
	v_lshl_add_u64 v[148:149], s[24:25], 0, v[136:137]
	s_add_i32 m0, s42, 0x2000
	s_nop 0
	global_load_lds_dwordx4 v[148:149], off
	v_lshl_add_u64 v[148:149], s[26:27], 0, v[130:131]
	s_mov_b32 m0, s64
	s_nop 0
	global_load_lds_dwordx4 v[148:149], off
	v_lshl_add_u64 v[148:149], s[26:27], 0, v[134:135]
	s_mov_b32 m0, s65
	s_nop 0
	global_load_lds_dwordx4 v[148:149], off
	s_waitcnt vmcnt(8)
	s_waitcnt lgkmcnt(0)
	s_barrier
	v_mfma_f32_16x16x32_bf16 v[62:65], v[144:147], v[188:191], v[62:65]
	v_mfma_f32_16x16x32_bf16 v[62:65], v[160:163], v[206:209], v[62:65]
	v_mfma_f32_16x16x32_bf16 v[58:61], v[168:171], v[206:209], v[58:61]
	v_mfma_f32_16x16x32_bf16 v[58:61], v[164:167], v[188:191], v[58:61]
	v_mfma_f32_16x16x32_bf16 v[42:45], v[164:167], v[210:213], v[42:45]
	v_mfma_f32_16x16x32_bf16 v[42:45], v[168:171], v[214:217], v[42:45]
	v_mfma_f32_16x16x32_bf16 v[46:49], v[160:163], v[214:217], v[46:49]
	v_mfma_f32_16x16x32_bf16 v[46:49], v[144:147], v[210:213], v[46:49]
	v_mfma_f32_16x16x32_bf16 v[30:33], v[144:147], v[218:221], v[30:33]
	v_mfma_f32_16x16x32_bf16 v[30:33], v[160:163], v[222:225], v[30:33]
	v_mfma_f32_16x16x32_bf16 v[26:29], v[168:171], v[222:225], v[26:29]
	v_mfma_f32_16x16x32_bf16 v[26:29], v[164:167], v[218:221], v[26:29]
	v_mfma_f32_16x16x32_bf16 v[10:13], v[164:167], v[226:229], v[10:13]
	v_mfma_f32_16x16x32_bf16 v[10:13], v[168:171], v[230:233], v[10:13]
	v_mfma_f32_16x16x32_bf16 v[14:17], v[160:163], v[230:233], v[14:17]
	v_mfma_f32_16x16x32_bf16 v[14:17], v[144:147], v[226:229], v[14:17]
	v_mfma_f32_16x16x32_bf16 v[54:57], v[172:175], v[188:191], v[54:57]
	v_mfma_f32_16x16x32_bf16 v[54:57], v[176:179], v[206:209], v[54:57]
	v_mfma_f32_16x16x32_bf16 v[50:53], v[184:187], v[206:209], v[50:53]
	v_mfma_f32_16x16x32_bf16 v[50:53], v[180:183], v[188:191], v[50:53]
	v_mfma_f32_16x16x32_bf16 v[34:37], v[180:183], v[210:213], v[34:37]
	v_mfma_f32_16x16x32_bf16 v[34:37], v[184:187], v[214:217], v[34:37]
	v_mfma_f32_16x16x32_bf16 v[38:41], v[176:179], v[214:217], v[38:41]
	v_mfma_f32_16x16x32_bf16 v[38:41], v[172:175], v[210:213], v[38:41]
	v_mfma_f32_16x16x32_bf16 v[22:25], v[172:175], v[218:221], v[22:25]
	v_mfma_f32_16x16x32_bf16 v[22:25], v[176:179], v[222:225], v[22:25]
	v_mfma_f32_16x16x32_bf16 v[18:21], v[184:187], v[222:225], v[18:21]
	v_mfma_f32_16x16x32_bf16 v[18:21], v[180:183], v[218:221], v[18:21]
	v_mfma_f32_16x16x32_bf16 v[2:5], v[180:183], v[226:229], v[2:5]
	v_mfma_f32_16x16x32_bf16 v[2:5], v[184:187], v[230:233], v[2:5]
	v_mfma_f32_16x16x32_bf16 v[6:9], v[176:179], v[230:233], v[6:9]
	v_mfma_f32_16x16x32_bf16 v[6:9], v[172:175], v[226:229], v[6:9]
	s_barrier
	s_add_i32 s71, s71, 2
	s_add_u32 s69, s69, 0x100
	s_addc_u32 s70, s70, 0
	s_cmp_gt_u32 s71, 13
	s_mov_b64 s[24:25], s[2:3]
	s_cbranch_scc1 .Lpeel_exit_0

; #define PG8_STAGE(bufoff, gbase, voff) do { _Pragma("unroll") for (int _i = 0; _i < 2; ++_i) \
;         __builtin_amdgcn_global_load_lds((const unsigned*)((const char*)(gbase) + (voff)[_i]), (PG8_LAS unsigned*)(lds + (bufoff) + ldsw + _i * 8192), 16, 0, 0); } while (0)
; #define PG8_WAIT_V(n) asm volatile("s_waitcnt vmcnt(" #n ")" ::: "memory")
; #define PG8_BAR __builtin_amdgcn_s_barrier()
; template <class Epi, class Sched, bool ALIGN_EPI = false, bool SP2 = false>
; __device__ __forceinline__ void gemm_phase(PG8_LAS unsigned char* lds, const Gemm g, const Sched& S, const Epi& E) {
;     ...
;     const int wid = __builtin_amdgcn_readfirstlane(tid >> 6), lane = tid & 63, wr = wid >> 2, wc = wid & 3, fr = lane & 15, fq = lane >> 4;
;     const int K = g.K, nt = K / BK;
;     unsigned voffA[2], voffB[2];
; #pragma unroll
;     for (int i = 0; i < 2; ++i) { int R, C; stage_rc(tid * 16 + i * 8192, R, C); const int Rb = Epi::PERM ? ((R & ~31) + perm32(R & 31)) : R;
;         voffA[i] = g.tiledA ? (unsigned)((C >> 5) * 8192 + R * 64 + (C & 31) * 2) : (unsigned)(R * K + C) * 2u; voffB[i] = (unsigned)(Rb * K + C) * 2u; }
;     const size_t kstep = (size_t)(BK * 2);
;     const size_t kstepA = g.tiledA ? (size_t)16384 : kstep;
;     const size_t hstep = (size_t)HALF * K * 2;
;     const size_t tstep = 2 * hstep;
;     const unsigned ldsw = (unsigned)wid * 1024u;
;     const int aoff = lds_byte(wr * 64 + fr, fq * 8), boff = lds_byte(wc * 32 + fr, fq * 8);
;     ...
;         PG8_STAGE(PG8_SB(0, 0), cB, voffB); PG8_STAGE(PG8_SB(0, 1), cB + hstep, voffB); PG8_STAGE(PG8_SA(0, 0), cA, voffA); PG8_STAGE(PG8_SA(0, 1), cA + hstep, voffA);
;         if (wr == 1) PG8_BAR;
;         PG8_WAIT_V(2); PG8_BAR;
;         PG8_STAGE(PG8_SB(1, 0), cB + kstep, voffB); PG8_STAGE(PG8_SA(1, 0), cA + kstepA, voffA); PG8_STAGE(PG8_SB(1, 1), cB + hstep + kstep, voffB);
;         PG8_WAIT_V(6); PG8_BAR;
.LBB0_296:
	s_and_b64 s[22:23], s[40:41], exec
	s_cselect_b32 s9, 0x8000, 0
	s_lshl_b32 s22, s9, 11
	s_add_u32 s44, s30, s22
	s_addc_u32 s45, s31, 0
	s_lshl_b32 s9, s9, 6
	v_readlane_b32 s22, v255, 16
	v_readlane_b32 s23, v255, 17
	s_add_u32 s22, s22, s9
	s_addc_u32 s23, s23, 0
	s_and_b32 s40, s5, 3
	s_add_i32 m0, s51, 0x18000
	v_lshl_add_u64 v[2:3], v[2:3], 0, s[38:39]
	s_lshr_b32 s55, s4, 6
	s_lshl_b32 s9, s8, 13
	s_lshl_b32 s41, s40, 12
	s_waitcnt vmcnt(2)
	s_barrier
	global_load_lds_dwordx4 v[2:3], off
	s_add_i32 m0, s51, 0x1a000
	s_add_u32 s4, s26, 0x4000
	v_mov_b32_e32 v161, v1
	v_lshl_add_u64 v[2:3], v[4:5], 0, s[38:39]
	s_addc_u32 s5, s27, 0
	s_add_i32 s56, s51, 0x8000
	v_mov_b32_e32 v163, v1
	global_load_lds_dwordx4 v[2:3], off
	v_lshl_add_u64 v[2:3], s[4:5], 0, v[160:161]
	s_mov_b32 m0, s56
	s_add_i32 s57, s51, 0xa000
	global_load_lds_dwordx4 v[2:3], off
	v_lshl_add_u64 v[2:3], s[4:5], 0, v[162:163]
	s_mov_b32 m0, s57
	v_and_b32_e32 v4, 15, v10
	global_load_lds_dwordx4 v[2:3], off
	s_add_i32 m0, s51, 0x1c000
	v_lshl_add_u64 v[2:3], v[6:7], 0, s[38:39]
	global_load_lds_dwordx4 v[2:3], off
	v_lshl_add_u64 v[2:3], v[8:9], 0, s[38:39]
	s_add_i32 m0, s51, 0x1e000
	v_lshlrev_b32_e32 v5, 2, v10
	global_load_lds_dwordx4 v[2:3], off
	v_bfe_u32 v3, v10, 4, 2
	v_lshlrev_b32_e32 v2, 4, v3
	v_lshl_or_b32 v186, s8, 6, v4
	v_lshl_or_b32 v4, v4, 6, v2
	v_and_b32_e32 v5, 32, v5
	v_bitop3_b32 v8, v4, s9, v5 bitop3:0xde
	v_bitop3_b32 v187, v4, s41, v5 bitop3:0xde
	v_lshlrev_b32_e32 v4, 5, v186
	v_cmp_eq_u32_e64 s[4:5], 0, v3
	v_ashrrev_i32_e32 v5, 31, v4
	v_mov_b32_e32 v3, v1
	v_lshl_add_u64 v[6:7], s[44:45], 0, v[2:3]
	v_lshlrev_b64 v[4:5], 1, v[4:5]
	v_lshl_add_u64 v[168:169], v[6:7], 0, v[4:5]
	v_lshl_add_u64 v[4:5], s[44:45], 0, v[4:5]
	s_add_i32 s59, s55, -2
	v_lshl_add_u64 v[178:179], v[4:5], 0, v[2:3]
	v_lshlrev_b32_e32 v2, 9, v15
	s_cmpk_lt_u32 s11, 0x100
	v_and_b32_e32 v2, 0xfffffc00, v2
	s_cselect_b64 s[42:43], -1, 0
	s_ashr_i32 s60, s14, 31
	s_ashr_i32 s61, s16, 31
	v_add_u32_e32 v2, v17, v2
	v_cndmask_b32_e64 v166, 1.0, 0.5, s[2:3]
	s_and_b64 s[2:3], s[6:7], exec
	v_add3_u32 v2, v2, v16, v18
	s_cselect_b32 s62, 6, 7
	s_lshr_b32 s2, s15, 1
	v_lshl_add_u64 v[180:181], s[12:13], 0, v[2:3]
	v_lshlrev_b32_e32 v2, 9, v11
	s_or_b32 s63, s2, 1
	s_mov_b64 s[2:3], 0x400
	v_and_b32_e32 v2, 0xfffffc00, v2
	s_waitcnt vmcnt(6)
	v_lshl_add_u64 v[170:171], v[168:169], 0, s[2:3]
	s_mov_b64 s[2:3], 0x800
	v_add_u32_e32 v2, v13, v2
	v_lshl_add_u64 v[172:173], v[168:169], 0, s[2:3]
	s_mov_b64 s[2:3], 0xc00
	v_add3_u32 v2, v2, v12, v14
	s_mov_b32 s58, 0
	s_mov_b32 s41, s35
	s_mov_b32 s11, s35
	v_lshl_add_u64 v[174:175], v[168:169], 0, s[2:3]
	v_mov_b32_e32 v176, v166
	v_mov_b32_e32 v177, v166
	v_lshl_add_u64 v[182:183], s[12:13], 0, v[2:3]
	v_add_u32_e32 v188, 0, v8
	s_waitcnt vmcnt(0)
	s_barrier
	s_branch .LBB0_299

; #define PG8_STAGE(bufoff, gbase, voff) do { _Pragma("unroll") for (int _i = 0; _i < 2; ++_i) \
;         __builtin_amdgcn_global_load_lds((const unsigned*)((const char*)(gbase) + (voff)[_i]), (PG8_LAS unsigned*)(lds + (bufoff) + ldsw + _i * 8192), 16, 0, 0); } while (0)
; #define PG8_LDA(dst, b, h) do { _Pragma("unroll") for (int m = 0; m < 4; ++m) _Pragma("unroll") for (int k = 0; k < 2; ++k) dst[m][k] = *(const PG8_LAS bf16x8*)(lds + PG8_SA(b, h) + aoff + m * 2048 + k * 1024); } while (0)
; #define PG8_LDB(dst, b, h) do { _Pragma("unroll") for (int n = 0; n < 2; ++n) _Pragma("unroll") for (int k = 0; k < 2; ++k) dst[n][k] = *(const PG8_LAS bf16x8*)(lds + PG8_SB(b, h) + boff + n * 2048 + k * 1024); } while (0)
; #define PG8_WAIT_V(n) asm volatile("s_waitcnt vmcnt(" #n ")" ::: "memory")
; #define PG8_WAIT_L(n) asm volatile("s_waitcnt lgkmcnt(" #n ")" ::: "memory")
; #define PG8_BAR __builtin_amdgcn_s_barrier()
; #define PG8_SCHED __builtin_amdgcn_sched_barrier(0)
; template <class Epi, class Sched, bool ALIGN_EPI = false, bool SP2 = false>
; __device__ __forceinline__ void gemm_phase(PG8_LAS unsigned char* lds, const Gemm g, const Sched& S, const Epi& E) {
;     ...
;         const char* nA = has_next ? (const char*)g.A + (size_t)nxt.pm * tstep : cA; const char* nB = has_next ? (const char*)g.Bt + (size_t)nxt.pn * tstep : cB;
;         for (int t = 0; t < nt; t += 2) {
;             const bool last = (t == nt - 2);
;             const char* a1 = cA + (size_t)(t + 1) * kstepA;
;             const char* a2 = last ? nA : cA + (size_t)(t + 2) * kstepA; const char* b2 = last ? nB : cB + (size_t)(t + 2) * kstep;
;             const char* a3 = a2 + kstepA; const char* b3 = b2 + kstep;
;             if (last && has_next) S.a_ready(nxt);
;             if constexpr (SP2) {
;             PG8_LDB(B0, 0, 0); PG8_LDB(B1, 0, 1); PG8_SCHED; PG8_LDA(At, 0, 0); PG8_STAGE(PG8_SA(1, 1), a1 + hstep, voffA);
;             PG8_WAIT_V(8); PG8_WAIT_L(0); PG8_BAR; PG8_MMA(0, 0, At, B0); PG8_MMA(0, 1, At, B1); PG8_BAR; PG8_SCHED;
;             PG8_LDA(At, 0, 1); PG8_STAGE(PG8_SB(0, 0), b2, voffB); PG8_STAGE(PG8_SB(0, 1), b2 + hstep, voffB); PG8_STAGE(PG8_SA(0, 0), a2, voffA);
;             PG8_WAIT_V(8); PG8_WAIT_L(0); PG8_BAR; PG8_MMA(1, 0, At, B0); PG8_MMA(1, 1, At, B1); PG8_BAR; PG8_SCHED;
.LBB0_309:
	s_add_u32 s47, s24, 0x100
	s_addc_u32 s48, s25, 0
	s_add_u32 s2, s26, 0x4000
	s_addc_u32 s3, s27, 0
	s_mov_b32 s24, 0
	s_add_i32 s49, s24, 2
	s_add_u32 s25, s2, 0x4000
	s_addc_u32 s26, s3, 0
	s_cmp_eq_u32 s59, s24
	s_cselect_b32 s27, s9, s26
	s_cselect_b32 s26, s8, s25
	s_cselect_b32 s66, s44, s47
	s_cselect_b32 s67, s45, s48
	s_add_u32 s24, s26, 0x4000
	s_addc_u32 s25, s27, 0
	s_add_i32 s65, 0, 0x14000
	v_add_u32_e32 v142, s76, v187
	v_add_u32_e32 v167, s65, v187
	ds_read_b128 v[130:133], v142
	ds_read_b128 v[134:137], v142 offset:1024
	ds_read_b128 v[138:141], v142 offset:2048
	ds_read_b128 v[142:145], v142 offset:3072
	ds_read_b128 v[146:149], v167
	ds_read_b128 v[150:153], v167 offset:1024
	ds_read_b128 v[206:209], v167 offset:2048
	ds_read_b128 v[210:213], v167 offset:3072
	v_lshl_add_u64 v[184:185], s[2:3], 0, v[182:183]
	s_add_i32 m0, s51, 0xc000
	ds_read_b128 v[214:217], v188
	ds_read_b128 v[218:221], v188 offset:1024
	ds_read_b128 v[222:225], v188 offset:2048
	ds_read_b128 v[226:229], v188 offset:3072
	ds_read_b128 v[230:233], v188 offset:4096
	ds_read_b128 v[234:237], v188 offset:5120
	ds_read_b128 v[238:241], v188 offset:6144
	ds_read_b128 v[242:245], v188 offset:7168
	global_load_lds_dwordx4 v[184:185], off
	v_lshl_add_u64 v[184:185], s[2:3], 0, v[180:181]
	s_add_i32 m0, s51, 0xe000
	s_nop 0
	global_load_lds_dwordx4 v[184:185], off
	s_waitcnt vmcnt(32)
	s_waitcnt lgkmcnt(0)
	s_barrier
	v_mfma_f32_16x16x32_bf16 v[126:129], v[130:133], v[214:217], 0
	v_mfma_f32_16x16x32_bf16 v[126:129], v[134:137], v[218:221], v[126:129]
	v_mfma_f32_16x16x32_bf16 v[122:125], v[142:145], v[218:221], 0
	v_mfma_f32_16x16x32_bf16 v[122:125], v[138:141], v[214:217], v[122:125]
	v_mfma_f32_16x16x32_bf16 v[106:109], v[138:141], v[222:225], 0
	v_mfma_f32_16x16x32_bf16 v[106:109], v[142:145], v[226:229], v[106:109]
	v_mfma_f32_16x16x32_bf16 v[110:113], v[134:137], v[226:229], 0
	v_mfma_f32_16x16x32_bf16 v[110:113], v[130:133], v[222:225], v[110:113]
	v_mfma_f32_16x16x32_bf16 v[94:97], v[130:133], v[230:233], 0
	v_mfma_f32_16x16x32_bf16 v[94:97], v[134:137], v[234:237], v[94:97]
	v_mfma_f32_16x16x32_bf16 v[90:93], v[142:145], v[234:237], 0
	v_mfma_f32_16x16x32_bf16 v[90:93], v[138:141], v[230:233], v[90:93]
	v_mfma_f32_16x16x32_bf16 v[74:77], v[138:141], v[238:241], 0
	v_mfma_f32_16x16x32_bf16 v[74:77], v[142:145], v[242:245], v[74:77]
	v_mfma_f32_16x16x32_bf16 v[78:81], v[134:137], v[242:245], 0
	v_mfma_f32_16x16x32_bf16 v[78:81], v[130:133], v[238:241], v[78:81]
	v_mfma_f32_16x16x32_bf16 v[118:121], v[146:149], v[214:217], 0
	v_mfma_f32_16x16x32_bf16 v[118:121], v[150:153], v[218:221], v[118:121]
	v_mfma_f32_16x16x32_bf16 v[114:117], v[210:213], v[218:221], 0
	v_mfma_f32_16x16x32_bf16 v[114:117], v[206:209], v[214:217], v[114:117]
	v_mfma_f32_16x16x32_bf16 v[98:101], v[206:209], v[222:225], 0
	v_mfma_f32_16x16x32_bf16 v[98:101], v[210:213], v[226:229], v[98:101]
	v_mfma_f32_16x16x32_bf16 v[102:105], v[150:153], v[226:229], 0
	v_mfma_f32_16x16x32_bf16 v[102:105], v[146:149], v[222:225], v[102:105]
	v_mfma_f32_16x16x32_bf16 v[86:89], v[146:149], v[230:233], 0
	v_mfma_f32_16x16x32_bf16 v[86:89], v[150:153], v[234:237], v[86:89]
	v_mfma_f32_16x16x32_bf16 v[82:85], v[210:213], v[234:237], 0
	v_mfma_f32_16x16x32_bf16 v[82:85], v[206:209], v[230:233], v[82:85]
	v_mfma_f32_16x16x32_bf16 v[66:69], v[206:209], v[238:241], 0
	v_mfma_f32_16x16x32_bf16 v[66:69], v[210:213], v[242:245], v[66:69]
	v_mfma_f32_16x16x32_bf16 v[70:73], v[150:153], v[242:245], 0
	v_mfma_f32_16x16x32_bf16 v[70:73], v[146:149], v[238:241], v[70:73]
	s_barrier
	s_add_i32 s68, s76, s50
	v_lshl_add_u64 v[184:185], s[66:67], 0, v[0:1]
	s_mov_b32 m0, s68
	ds_read_b128 v[214:217], v188 offset:16384
	ds_read_b128 v[218:221], v188 offset:17408
	ds_read_b128 v[222:225], v188 offset:18432
	ds_read_b128 v[226:229], v188 offset:19456
	ds_read_b128 v[230:233], v188 offset:20480
	ds_read_b128 v[234:237], v188 offset:21504
	ds_read_b128 v[238:241], v188 offset:22528
	ds_read_b128 v[242:245], v188 offset:23552
	global_load_lds_dwordx4 v[184:185], off
	s_add_i32 m0, s68, 0x2000
	v_lshl_add_u64 v[190:191], s[66:67], 0, v[164:165]
	s_add_u32 s66, s66, s12
	s_addc_u32 s67, s67, 0
	s_add_i32 s65, s65, s50
	global_load_lds_dwordx4 v[190:191], off
	v_lshl_add_u64 v[246:247], s[66:67], 0, v[0:1]
	s_mov_b32 m0, s65
	v_lshl_add_u64 v[248:249], s[66:67], 0, v[164:165]
	global_load_lds_dwordx4 v[246:247], off
	s_add_i32 m0, s65, 0x2000
	v_lshl_add_u64 v[250:251], s[26:27], 0, v[160:161]
	global_load_lds_dwordx4 v[248:249], off
	s_mov_b32 m0, s51
	s_nop 0
	global_load_lds_dwordx4 v[250:251], off
	v_lshl_add_u64 v[250:251], s[26:27], 0, v[162:163]
	s_mov_b32 m0, s52
	s_nop 0
	global_load_lds_dwordx4 v[250:251], off
	s_waitcnt vmcnt(32)
	s_waitcnt lgkmcnt(0)
	s_barrier
; #define PG8_STAGE(bufoff, gbase, voff) do { _Pragma("unroll") for (int _i = 0; _i < 2; ++_i) \
;         __builtin_amdgcn_global_load_lds((const unsigned*)((const char*)(gbase) + (voff)[_i]), (PG8_LAS unsigned*)(lds + (bufoff) + ldsw + _i * 8192), 16, 0, 0); } while (0)
; #define PG8_LDA(dst, b, h) do { _Pragma("unroll") for (int m = 0; m < 4; ++m) _Pragma("unroll") for (int k = 0; k < 2; ++k) dst[m][k] = *(const PG8_LAS bf16x8*)(lds + PG8_SA(b, h) + aoff + m * 2048 + k * 1024); } while (0)
; #define PG8_LDB(dst, b, h) do { _Pragma("unroll") for (int n = 0; n < 2; ++n) _Pragma("unroll") for (int k = 0; k < 2; ++k) dst[n][k] = *(const PG8_LAS bf16x8*)(lds + PG8_SB(b, h) + boff + n * 2048 + k * 1024); } while (0)
; #define PG8_MMA(ai, bj, At, Bt) do { __builtin_amdgcn_s_setprio(1); _Pragma("unroll") for (int m = 0; m < 4; ++m) _Pragma("unroll") for (int n = 0; n < 2; ++n) _Pragma("unroll") for (int k = 0; k < 2; ++k) \
;         acc[ai][bj][m][n] = __builtin_amdgcn_mfma_f32_16x16x32_bf16(Bt[n][k], At[m][k], acc[ai][bj][m][n], 0, 0, 0); __builtin_amdgcn_s_setprio(0); } while (0)
; #define PG8_WAIT_V(n) asm volatile("s_waitcnt vmcnt(" #n ")" ::: "memory")
; #define PG8_WAIT_L(n) asm volatile("s_waitcnt lgkmcnt(" #n ")" ::: "memory")
; #define PG8_BAR __builtin_amdgcn_s_barrier()
; #define PG8_SCHED __builtin_amdgcn_sched_barrier(0)
; template <class Epi, class Sched, bool ALIGN_EPI = false, bool SP2 = false>
; __device__ __forceinline__ void gemm_phase(PG8_LAS unsigned char* lds, const Gemm g, const Sched& S, const Epi& E) {
;     ...
;             PG8_WAIT_V(8); PG8_WAIT_L(0); PG8_BAR; PG8_MMA(1, 0, At, B0); PG8_MMA(1, 1, At, B1); PG8_BAR; PG8_SCHED;
;             PG8_LDB(B0, 1, 0); PG8_LDB(B1, 1, 1); PG8_SCHED; PG8_LDA(At, 1, 0); PG8_STAGE(PG8_SA(0, 1), a2 + hstep, voffA);
;             PG8_WAIT_V(8); PG8_WAIT_L(0); PG8_BAR; PG8_MMA(0, 0, At, B0); PG8_MMA(0, 1, At, B1); PG8_BAR; PG8_SCHED;
	v_mfma_f32_16x16x32_bf16 v[62:65], v[130:133], v[214:217], 0
	v_mfma_f32_16x16x32_bf16 v[62:65], v[134:137], v[218:221], v[62:65]
	v_mfma_f32_16x16x32_bf16 v[58:61], v[142:145], v[218:221], 0
	v_mfma_f32_16x16x32_bf16 v[58:61], v[138:141], v[214:217], v[58:61]
	v_mfma_f32_16x16x32_bf16 v[42:45], v[138:141], v[222:225], 0
	v_mfma_f32_16x16x32_bf16 v[42:45], v[142:145], v[226:229], v[42:45]
	v_mfma_f32_16x16x32_bf16 v[46:49], v[134:137], v[226:229], 0
	v_mfma_f32_16x16x32_bf16 v[46:49], v[130:133], v[222:225], v[46:49]
	v_mfma_f32_16x16x32_bf16 v[30:33], v[130:133], v[230:233], 0
	v_mfma_f32_16x16x32_bf16 v[30:33], v[134:137], v[234:237], v[30:33]
	v_mfma_f32_16x16x32_bf16 v[26:29], v[142:145], v[234:237], 0
	v_mfma_f32_16x16x32_bf16 v[26:29], v[138:141], v[230:233], v[26:29]
	v_mfma_f32_16x16x32_bf16 v[10:13], v[138:141], v[238:241], 0
	v_mfma_f32_16x16x32_bf16 v[10:13], v[142:145], v[242:245], v[10:13]
	v_mfma_f32_16x16x32_bf16 v[14:17], v[134:137], v[242:245], 0
	v_mfma_f32_16x16x32_bf16 v[14:17], v[130:133], v[238:241], v[14:17]
	v_mfma_f32_16x16x32_bf16 v[54:57], v[146:149], v[214:217], 0
	v_mfma_f32_16x16x32_bf16 v[54:57], v[150:153], v[218:221], v[54:57]
	v_mfma_f32_16x16x32_bf16 v[50:53], v[210:213], v[218:221], 0
	v_mfma_f32_16x16x32_bf16 v[50:53], v[206:209], v[214:217], v[50:53]
	v_mfma_f32_16x16x32_bf16 v[34:37], v[206:209], v[222:225], 0
	v_mfma_f32_16x16x32_bf16 v[34:37], v[210:213], v[226:229], v[34:37]
	v_mfma_f32_16x16x32_bf16 v[38:41], v[150:153], v[226:229], 0
	v_mfma_f32_16x16x32_bf16 v[38:41], v[146:149], v[222:225], v[38:41]
	v_mfma_f32_16x16x32_bf16 v[22:25], v[146:149], v[230:233], 0
	v_mfma_f32_16x16x32_bf16 v[22:25], v[150:153], v[234:237], v[22:25]
	v_mfma_f32_16x16x32_bf16 v[18:21], v[210:213], v[234:237], 0
	v_mfma_f32_16x16x32_bf16 v[18:21], v[206:209], v[230:233], v[18:21]
	v_mfma_f32_16x16x32_bf16 v[2:5], v[206:209], v[238:241], 0
	v_mfma_f32_16x16x32_bf16 v[2:5], v[210:213], v[242:245], v[2:5]
	v_mfma_f32_16x16x32_bf16 v[6:9], v[150:153], v[242:245], 0
	v_mfma_f32_16x16x32_bf16 v[6:9], v[146:149], v[238:241], v[6:9]
	s_barrier
	s_add_i32 s65, 0, 0x18000
	s_add_i32 s66, 0, 0x1c000
	v_add_u32_e32 v142, s65, v187
	v_add_u32_e32 v167, s66, v187
	ds_read_b128 v[130:133], v142
	ds_read_b128 v[134:137], v142 offset:1024
	ds_read_b128 v[138:141], v142 offset:2048
	ds_read_b128 v[142:145], v142 offset:3072
	ds_read_b128 v[146:149], v167
	ds_read_b128 v[150:153], v167 offset:1024
	ds_read_b128 v[206:209], v167 offset:2048
	ds_read_b128 v[210:213], v167 offset:3072
	s_add_u32 s26, s26, s12
	s_addc_u32 s27, s27, 0
	s_mov_b32 m0, s53
	v_lshl_add_u64 v[250:251], s[26:27], 0, v[160:161]
	ds_read_b128 v[214:217], v188 offset:32768
	ds_read_b128 v[218:221], v188 offset:33792
	ds_read_b128 v[222:225], v188 offset:34816
	ds_read_b128 v[226:229], v188 offset:35840
	ds_read_b128 v[230:233], v188 offset:36864
	ds_read_b128 v[234:237], v188 offset:37888
	ds_read_b128 v[238:241], v188 offset:38912
	ds_read_b128 v[242:245], v188 offset:39936
	global_load_lds_dwordx4 v[250:251], off
	v_lshl_add_u64 v[250:251], s[26:27], 0, v[162:163]
	s_mov_b32 m0, s54
	s_nop 0
	global_load_lds_dwordx4 v[250:251], off
	s_waitcnt vmcnt(8)
	s_waitcnt lgkmcnt(0)
	s_barrier
	v_mfma_f32_16x16x32_bf16 v[126:129], v[130:133], v[214:217], v[126:129]
	v_mfma_f32_16x16x32_bf16 v[126:129], v[134:137], v[218:221], v[126:129]
	v_mfma_f32_16x16x32_bf16 v[122:125], v[142:145], v[218:221], v[122:125]
	v_mfma_f32_16x16x32_bf16 v[122:125], v[138:141], v[214:217], v[122:125]
	v_mfma_f32_16x16x32_bf16 v[106:109], v[138:141], v[222:225], v[106:109]
	v_mfma_f32_16x16x32_bf16 v[106:109], v[142:145], v[226:229], v[106:109]
	v_mfma_f32_16x16x32_bf16 v[110:113], v[134:137], v[226:229], v[110:113]
	v_mfma_f32_16x16x32_bf16 v[110:113], v[130:133], v[222:225], v[110:113]
	v_mfma_f32_16x16x32_bf16 v[94:97], v[130:133], v[230:233], v[94:97]
	v_mfma_f32_16x16x32_bf16 v[94:97], v[134:137], v[234:237], v[94:97]
	v_mfma_f32_16x16x32_bf16 v[90:93], v[142:145], v[234:237], v[90:93]
	v_mfma_f32_16x16x32_bf16 v[90:93], v[138:141], v[230:233], v[90:93]
	v_mfma_f32_16x16x32_bf16 v[74:77], v[138:141], v[238:241], v[74:77]
	v_mfma_f32_16x16x32_bf16 v[74:77], v[142:145], v[242:245], v[74:77]
	v_mfma_f32_16x16x32_bf16 v[78:81], v[134:137], v[242:245], v[78:81]
	v_mfma_f32_16x16x32_bf16 v[78:81], v[130:133], v[238:241], v[78:81]
	v_mfma_f32_16x16x32_bf16 v[118:121], v[146:149], v[214:217], v[118:121]
	v_mfma_f32_16x16x32_bf16 v[118:121], v[150:153], v[218:221], v[118:121]
	v_mfma_f32_16x16x32_bf16 v[114:117], v[210:213], v[218:221], v[114:117]
	v_mfma_f32_16x16x32_bf16 v[114:117], v[206:209], v[214:217], v[114:117]
	v_mfma_f32_16x16x32_bf16 v[98:101], v[206:209], v[222:225], v[98:101]
	v_mfma_f32_16x16x32_bf16 v[98:101], v[210:213], v[226:229], v[98:101]
	v_mfma_f32_16x16x32_bf16 v[102:105], v[150:153], v[226:229], v[102:105]
	v_mfma_f32_16x16x32_bf16 v[102:105], v[146:149], v[222:225], v[102:105]
	v_mfma_f32_16x16x32_bf16 v[86:89], v[146:149], v[230:233], v[86:89]
	v_mfma_f32_16x16x32_bf16 v[86:89], v[150:153], v[234:237], v[86:89]
	v_mfma_f32_16x16x32_bf16 v[82:85], v[210:213], v[234:237], v[82:85]
	v_mfma_f32_16x16x32_bf16 v[82:85], v[206:209], v[230:233], v[82:85]
	v_mfma_f32_16x16x32_bf16 v[66:69], v[206:209], v[238:241], v[66:69]
	v_mfma_f32_16x16x32_bf16 v[66:69], v[210:213], v[242:245], v[66:69]
	v_mfma_f32_16x16x32_bf16 v[70:73], v[150:153], v[242:245], v[70:73]
	v_mfma_f32_16x16x32_bf16 v[70:73], v[146:149], v[238:241], v[70:73]
	s_barrier
; #define PG8_STAGE(bufoff, gbase, voff) do { _Pragma("unroll") for (int _i = 0; _i < 2; ++_i) \
;         __builtin_amdgcn_global_load_lds((const unsigned*)((const char*)(gbase) + (voff)[_i]), (PG8_LAS unsigned*)(lds + (bufoff) + ldsw + _i * 8192), 16, 0, 0); } while (0)
; #define PG8_LDA(dst, b, h) do { _Pragma("unroll") for (int m = 0; m < 4; ++m) _Pragma("unroll") for (int k = 0; k < 2; ++k) dst[m][k] = *(const PG8_LAS bf16x8*)(lds + PG8_SA(b, h) + aoff + m * 2048 + k * 1024); } while (0)
; #define PG8_MMA(ai, bj, At, Bt) do { __builtin_amdgcn_s_setprio(1); _Pragma("unroll") for (int m = 0; m < 4; ++m) _Pragma("unroll") for (int n = 0; n < 2; ++n) _Pragma("unroll") for (int k = 0; k < 2; ++k) \
;         acc[ai][bj][m][n] = __builtin_amdgcn_mfma_f32_16x16x32_bf16(Bt[n][k], At[m][k], acc[ai][bj][m][n], 0, 0, 0); __builtin_amdgcn_s_setprio(0); } while (0)
; #define PG8_WAIT_V(n) asm volatile("s_waitcnt vmcnt(" #n ")" ::: "memory")
; #define PG8_WAIT_L(n) asm volatile("s_waitcnt lgkmcnt(" #n ")" ::: "memory")
; #define PG8_BAR __builtin_amdgcn_s_barrier()
; #define PG8_SCHED __builtin_amdgcn_sched_barrier(0)
; template <class Epi, class Sched, bool ALIGN_EPI = false, bool SP2 = false>
; __device__ __forceinline__ void gemm_phase(PG8_LAS unsigned char* lds, const Gemm g, const Sched& S, const Epi& E) {
;     ...
;             PG8_LDA(At, 1, 1); PG8_STAGE(PG8_SB(1, 0), b3, voffB); PG8_STAGE(PG8_SB(1, 1), b3 + hstep, voffB); PG8_STAGE(PG8_SA(1, 0), a3, voffA);
;             PG8_WAIT_V(8); PG8_WAIT_L(0); PG8_BAR; PG8_MMA(1, 0, At, B0); PG8_MMA(1, 1, At, B1); PG8_BAR; PG8_SCHED;
	s_add_i32 s26, s65, s50
	v_lshl_add_u64 v[184:185], v[184:185], 0, s[38:39]
	s_mov_b32 m0, s26
	ds_read_b128 v[214:217], v188 offset:49152
	ds_read_b128 v[218:221], v188 offset:50176
	ds_read_b128 v[222:225], v188 offset:51200
	ds_read_b128 v[226:229], v188 offset:52224
	ds_read_b128 v[230:233], v188 offset:53248
	ds_read_b128 v[234:237], v188 offset:54272
	ds_read_b128 v[238:241], v188 offset:55296
	ds_read_b128 v[242:245], v188 offset:56320
	global_load_lds_dwordx4 v[184:185], off
	v_lshl_add_u64 v[184:185], v[190:191], 0, s[38:39]
	s_add_i32 m0, s26, 0x2000
	s_add_i32 s26, s66, s50
	global_load_lds_dwordx4 v[184:185], off
	v_lshl_add_u64 v[184:185], v[246:247], 0, s[38:39]
	s_mov_b32 m0, s26
	s_nop 0
	global_load_lds_dwordx4 v[184:185], off
	v_lshl_add_u64 v[184:185], v[248:249], 0, s[38:39]
	s_add_i32 m0, s26, 0x2000
	s_nop 0
	global_load_lds_dwordx4 v[184:185], off
	v_lshl_add_u64 v[184:185], s[24:25], 0, v[160:161]
	s_mov_b32 m0, s56
	s_nop 0
	global_load_lds_dwordx4 v[184:185], off
	v_lshl_add_u64 v[184:185], s[24:25], 0, v[162:163]
	s_mov_b32 m0, s57
	s_nop 0
	global_load_lds_dwordx4 v[184:185], off
	s_waitcnt vmcnt(8)
	s_waitcnt lgkmcnt(0)
	s_barrier
	v_mfma_f32_16x16x32_bf16 v[62:65], v[130:133], v[214:217], v[62:65]
	v_mfma_f32_16x16x32_bf16 v[62:65], v[134:137], v[218:221], v[62:65]
	v_mfma_f32_16x16x32_bf16 v[58:61], v[142:145], v[218:221], v[58:61]
	v_mfma_f32_16x16x32_bf16 v[58:61], v[138:141], v[214:217], v[58:61]
	v_mfma_f32_16x16x32_bf16 v[42:45], v[138:141], v[222:225], v[42:45]
	v_mfma_f32_16x16x32_bf16 v[42:45], v[142:145], v[226:229], v[42:45]
	v_mfma_f32_16x16x32_bf16 v[46:49], v[134:137], v[226:229], v[46:49]
	v_mfma_f32_16x16x32_bf16 v[46:49], v[130:133], v[222:225], v[46:49]
	v_mfma_f32_16x16x32_bf16 v[30:33], v[130:133], v[230:233], v[30:33]
	v_mfma_f32_16x16x32_bf16 v[30:33], v[134:137], v[234:237], v[30:33]
	v_mfma_f32_16x16x32_bf16 v[26:29], v[142:145], v[234:237], v[26:29]
	v_mfma_f32_16x16x32_bf16 v[26:29], v[138:141], v[230:233], v[26:29]
	v_mfma_f32_16x16x32_bf16 v[10:13], v[138:141], v[238:241], v[10:13]
	v_mfma_f32_16x16x32_bf16 v[10:13], v[142:145], v[242:245], v[10:13]
	v_mfma_f32_16x16x32_bf16 v[14:17], v[134:137], v[242:245], v[14:17]
	v_mfma_f32_16x16x32_bf16 v[14:17], v[130:133], v[238:241], v[14:17]
	v_mfma_f32_16x16x32_bf16 v[54:57], v[146:149], v[214:217], v[54:57]
	v_mfma_f32_16x16x32_bf16 v[54:57], v[150:153], v[218:221], v[54:57]
	v_mfma_f32_16x16x32_bf16 v[50:53], v[210:213], v[218:221], v[50:53]
	v_mfma_f32_16x16x32_bf16 v[50:53], v[206:209], v[214:217], v[50:53]
	v_mfma_f32_16x16x32_bf16 v[34:37], v[206:209], v[222:225], v[34:37]
	v_mfma_f32_16x16x32_bf16 v[34:37], v[210:213], v[226:229], v[34:37]
	v_mfma_f32_16x16x32_bf16 v[38:41], v[150:153], v[226:229], v[38:41]
	v_mfma_f32_16x16x32_bf16 v[38:41], v[146:149], v[222:225], v[38:41]
	v_mfma_f32_16x16x32_bf16 v[22:25], v[146:149], v[230:233], v[22:25]
	v_mfma_f32_16x16x32_bf16 v[22:25], v[150:153], v[234:237], v[22:25]
	v_mfma_f32_16x16x32_bf16 v[18:21], v[210:213], v[234:237], v[18:21]
	v_mfma_f32_16x16x32_bf16 v[18:21], v[206:209], v[230:233], v[18:21]
	v_mfma_f32_16x16x32_bf16 v[2:5], v[206:209], v[238:241], v[2:5]
	v_mfma_f32_16x16x32_bf16 v[2:5], v[210:213], v[242:245], v[2:5]
	v_mfma_f32_16x16x32_bf16 v[6:9], v[150:153], v[242:245], v[6:9]
	v_mfma_f32_16x16x32_bf16 v[6:9], v[146:149], v[238:241], v[6:9]
	s_barrier
	s_add_u32 s47, s47, 0x100
	s_addc_u32 s48, s48, 0
	s_add_u32 s2, s2, 0x8000
	s_addc_u32 s3, s3, 0
	s_cmp_ge_u32 s49, s55
	s_mov_b32 s24, s49
	s_cbranch_scc1 .Lpeel_exit_1
